# attention unit epilogue: the 16 sub-layer-norm weight vectors loaded together up front instead of 2 per store behind vmcnt(0) ladders
# speedup vs baseline: 1.0061x; 1.0061x over previous
; #define LAS __attribute__((address_space(3)))
; #define AT_EXP(c) do { ev_[(c) & 1].x = __builtin_amdgcn_exp2f(xs_[(c) & 1].x); ev_[(c) & 1].y = __builtin_amdgcn_exp2f(xs_[(c) & 1].y); } while (0)
; __device__ __forceinline__ void attn_unit(ldsp lds, const bf16* QK, const bf16* VT, bf16* MIX, const float* subln, float lam, int tokbase, int L, int h, int qb, int tid, int wid, int lane) {
;     ...
;     const float linv = 1.f / (l_reg + __shfl_xor(l_reg, 32));
;     LAS float* ex = (LAS float*)(lds + AT_EX) + (size_t)(g * 32 + n) * AT_EXP;
;     if (j == 1) {
;         const float sc = linv * lam;
; #pragma unroll
;         for (int t = 0; t < 4; ++t)
; #pragma unroll
;             for (int r4 = 0; r4 < 4; ++r4) { const int dv = 32 * t + 8 * r4 + 4 * hi;
;                 *(LAS f32x4*)(ex + dv) = (f32x4){o[t][4 * r4] * sc, o[t][4 * r4 + 1] * sc, o[t][4 * r4 + 2] * sc, o[t][4 * r4 + 3] * sc}; }
;     }
;     __syncthreads();
;     if (j == 0) {
;         float ss = 0.f;
; #pragma unroll
;         for (int t = 0; t < 4; ++t)
; #pragma unroll
;             for (int r4 = 0; r4 < 4; ++r4) { const int dv = 32 * t + 8 * r4 + 4 * hi; const f32x4 e = *(const LAS f32x4*)(ex + dv);
; #pragma unroll
;                 for (int k = 0; k < 4; ++k) { const float v = o[t][4 * r4 + k] * linv - e[k]; o[t][4 * r4 + k] = v; ss += v * v; } }
;         ss += __shfl_xor(ss, 32);
;         const float rs = 0.8f / sqrtf(ss * (1.f / 128.f) + 1e-5f);
;         bf16* orow = MIX + (size_t)(tokbase + q0 + n) * D + 512 + h * 128;
; #pragma unroll
;         for (int t = 0; t < 4; ++t)
; #pragma unroll
;             for (int p2 = 0; p2 < 2; ++p2) {
;                 u32x2 eo[2];
; #pragma unroll
;                 for (int q = 0; q < 2; ++q) { const int r4 = 2 * p2 + q, dv = 32 * t + 8 * r4 + 4 * hi; const f32x4 w = *(const f32x4*)(subln + dv);
.LBB0_1023:
	s_andn2_b64 vcc, exec, s[64:65]
	s_waitcnt lgkmcnt(0)
	s_barrier
	s_cbranch_vccnz .LBB0_999
	ds_read_b128 v[70:73], v189
	ds_read_b128 v[74:77], v189 offset:32
	ds_read_b128 v[78:81], v189 offset:64
	ds_read_b128 v[82:85], v189 offset:96
	ds_read_b128 v[86:89], v189 offset:128
	ds_read_b128 v[90:93], v189 offset:160
	ds_read_b128 v[94:97], v189 offset:192
	ds_read_b128 v[98:101], v189 offset:224
	ds_read_b128 v[102:105], v189 offset:256
	ds_read_b128 v[106:109], v189 offset:288
	s_waitcnt vmcnt(3)
	ds_read_b128 v[110:113], v189 offset:448
	s_waitcnt vmcnt(2)
	ds_read_b128 v[114:117], v189 offset:320
	s_waitcnt vmcnt(0)
	ds_read_b128 v[118:121], v189 offset:352
	ds_read_b128 v[122:125], v189 offset:480
	ds_read_b128 v[126:129], v189 offset:384
	ds_read_b128 v[130:133], v189 offset:416
	s_waitcnt lgkmcnt(14)
	v_pk_fma_f32 v[142:143], v[48:49], v[68:69], v[70:71] op_sel_hi:[1,0,1] neg_lo:[0,0,1] neg_hi:[0,0,1]
	v_pk_fma_f32 v[138:139], v[50:51], v[68:69], v[72:73] op_sel_hi:[1,0,1] neg_lo:[0,0,1] neg_hi:[0,0,1]
	v_pk_mul_f32 v[144:145], v[142:143], v[142:143]
	s_waitcnt lgkmcnt(5)
	v_pk_fma_f32 v[64:65], v[10:11], v[68:69], v[112:113] op_sel_hi:[1,0,1] neg_lo:[0,0,1] neg_hi:[0,0,1]
	s_waitcnt lgkmcnt(2)
	v_pk_fma_f32 v[66:67], v[12:13], v[68:69], v[122:123] op_sel_hi:[1,0,1] neg_lo:[0,0,1] neg_hi:[0,0,1]
	v_pk_fma_f32 v[14:15], v[14:15], v[68:69], v[124:125] op_sel_hi:[1,0,1] neg_lo:[0,0,1] neg_hi:[0,0,1]
	v_pk_mul_f32 v[140:141], v[138:139], v[138:139]
	v_pk_fma_f32 v[72:73], v[54:55], v[68:69], v[76:77] op_sel_hi:[1,0,1] neg_lo:[0,0,1] neg_hi:[0,0,1]
	v_pk_fma_f32 v[74:75], v[52:53], v[68:69], v[74:75] op_sel_hi:[1,0,1] neg_lo:[0,0,1] neg_hi:[0,0,1]
	v_pk_fma_f32 v[70:71], v[58:59], v[68:69], v[80:81] op_sel_hi:[1,0,1] neg_lo:[0,0,1] neg_hi:[0,0,1]
	v_pk_fma_f32 v[58:59], v[62:63], v[68:69], v[84:85] op_sel_hi:[1,0,1] neg_lo:[0,0,1] neg_hi:[0,0,1]
	v_pk_fma_f32 v[62:63], v[56:57], v[68:69], v[78:79] op_sel_hi:[1,0,1] neg_lo:[0,0,1] neg_hi:[0,0,1]
	v_pk_fma_f32 v[60:61], v[60:61], v[68:69], v[82:83] op_sel_hi:[1,0,1] neg_lo:[0,0,1] neg_hi:[0,0,1]
	v_pk_fma_f32 v[52:53], v[34:35], v[68:69], v[88:89] op_sel_hi:[1,0,1] neg_lo:[0,0,1] neg_hi:[0,0,1]
	v_pk_fma_f32 v[50:51], v[38:39], v[68:69], v[92:93] op_sel_hi:[1,0,1] neg_lo:[0,0,1] neg_hi:[0,0,1]
	v_pk_fma_f32 v[54:55], v[32:33], v[68:69], v[86:87] op_sel_hi:[1,0,1] neg_lo:[0,0,1] neg_hi:[0,0,1]
	v_pk_fma_f32 v[56:57], v[36:37], v[68:69], v[90:91] op_sel_hi:[1,0,1] neg_lo:[0,0,1] neg_hi:[0,0,1]
	v_pk_fma_f32 v[48:49], v[42:43], v[68:69], v[96:97] op_sel_hi:[1,0,1] neg_lo:[0,0,1] neg_hi:[0,0,1]
	v_pk_fma_f32 v[42:43], v[46:47], v[68:69], v[100:101] op_sel_hi:[1,0,1] neg_lo:[0,0,1] neg_hi:[0,0,1]
	v_pk_fma_f32 v[40:41], v[40:41], v[68:69], v[94:95] op_sel_hi:[1,0,1] neg_lo:[0,0,1] neg_hi:[0,0,1]
	v_pk_fma_f32 v[44:45], v[44:45], v[68:69], v[98:99] op_sel_hi:[1,0,1] neg_lo:[0,0,1] neg_hi:[0,0,1]
	v_pk_fma_f32 v[34:35], v[18:19], v[68:69], v[104:105] op_sel_hi:[1,0,1] neg_lo:[0,0,1] neg_hi:[0,0,1]
	v_pk_fma_f32 v[32:33], v[22:23], v[68:69], v[108:109] op_sel_hi:[1,0,1] neg_lo:[0,0,1] neg_hi:[0,0,1]
	v_pk_fma_f32 v[36:37], v[16:17], v[68:69], v[102:103] op_sel_hi:[1,0,1] neg_lo:[0,0,1] neg_hi:[0,0,1]
	v_pk_fma_f32 v[38:39], v[20:21], v[68:69], v[106:107] op_sel_hi:[1,0,1] neg_lo:[0,0,1] neg_hi:[0,0,1]
	v_pk_fma_f32 v[22:23], v[26:27], v[68:69], v[116:117] op_sel_hi:[1,0,1] neg_lo:[0,0,1] neg_hi:[0,0,1]
	v_pk_fma_f32 v[20:21], v[30:31], v[68:69], v[120:121] op_sel_hi:[1,0,1] neg_lo:[0,0,1] neg_hi:[0,0,1]
	v_pk_fma_f32 v[24:25], v[24:25], v[68:69], v[114:115] op_sel_hi:[1,0,1] neg_lo:[0,0,1] neg_hi:[0,0,1]
	v_pk_fma_f32 v[26:27], v[28:29], v[68:69], v[118:119] op_sel_hi:[1,0,1] neg_lo:[0,0,1] neg_hi:[0,0,1]
	s_waitcnt lgkmcnt(1)
	v_pk_fma_f32 v[16:17], v[2:3], v[68:69], v[128:129] op_sel_hi:[1,0,1] neg_lo:[0,0,1] neg_hi:[0,0,1]
	s_waitcnt lgkmcnt(0)
	v_pk_fma_f32 v[6:7], v[6:7], v[68:69], v[132:133] op_sel_hi:[1,0,1] neg_lo:[0,0,1] neg_hi:[0,0,1]
	v_pk_fma_f32 v[18:19], v[0:1], v[68:69], v[126:127] op_sel_hi:[1,0,1] neg_lo:[0,0,1] neg_hi:[0,0,1]
	v_pk_fma_f32 v[4:5], v[4:5], v[68:69], v[130:131] op_sel_hi:[1,0,1] neg_lo:[0,0,1] neg_hi:[0,0,1]
	v_pk_fma_f32 v[0:1], v[8:9], v[68:69], v[110:111] op_sel_hi:[1,0,1] neg_lo:[0,0,1] neg_hi:[0,0,1]
	v_add_f32_e32 v68, v144, v145
	v_add_f32_e32 v68, v140, v68
	v_pk_mul_f32 v[146:147], v[74:75], v[74:75]
	v_add_f32_e32 v68, v141, v68
	v_add_f32_e32 v68, v146, v68
	v_pk_mul_f32 v[76:77], v[72:73], v[72:73]
	v_add_f32_e32 v68, v147, v68
	v_add_f32_e32 v68, v76, v68
	v_pk_mul_f32 v[78:79], v[62:63], v[62:63]
	v_add_f32_e32 v68, v77, v68
	v_add_f32_e32 v68, v78, v68
	v_pk_mul_f32 v[80:81], v[70:71], v[70:71]
	v_add_f32_e32 v68, v79, v68
	v_add_f32_e32 v68, v80, v68
	v_pk_mul_f32 v[82:83], v[60:61], v[60:61]
	v_add_f32_e32 v68, v81, v68
	v_add_f32_e32 v68, v82, v68
	v_pk_mul_f32 v[84:85], v[58:59], v[58:59]
	v_add_f32_e32 v68, v83, v68
	v_add_f32_e32 v68, v84, v68
	v_pk_mul_f32 v[86:87], v[54:55], v[54:55]
	v_add_f32_e32 v68, v85, v68
	v_add_f32_e32 v68, v86, v68
	v_pk_mul_f32 v[88:89], v[52:53], v[52:53]
	v_add_f32_e32 v68, v87, v68
	v_add_f32_e32 v68, v88, v68
	v_pk_mul_f32 v[90:91], v[56:57], v[56:57]
	v_add_f32_e32 v68, v89, v68
	v_add_f32_e32 v68, v90, v68
	global_load_dwordx4 v[122:125], v[172:173], off
	global_load_dwordx4 v[10:13], v[172:173], off offset:32
	global_load_dwordx4 v[148:151], v[172:173], off offset:64
	global_load_dwordx4 v[152:155], v[172:173], off offset:96
	global_load_dwordx4 v[156:159], v[172:173], off offset:128
	global_load_dwordx4 v[196:199], v[172:173], off offset:160
	global_load_dwordx4 v[200:203], v[172:173], off offset:192
; #define LAS __attribute__((address_space(3)))
; __device__ __forceinline__ unsigned pk2(float lo, float hi) { return f2bf(lo) | (f2bf(hi) << 16); }
; __device__ __forceinline__ void attn_unit(ldsp lds, const bf16* QK, const bf16* VT, bf16* MIX, const float* subln, float lam, int tokbase, int L, int h, int qb, int tid, int wid, int lane) {
;     ...
;         float ss = 0.f;
; #pragma unroll
;         for (int t = 0; t < 4; ++t)
; #pragma unroll
;             for (int r4 = 0; r4 < 4; ++r4) { const int dv = 32 * t + 8 * r4 + 4 * hi; const f32x4 e = *(const LAS f32x4*)(ex + dv);
; #pragma unroll
;                 for (int k = 0; k < 4; ++k) { const float v = o[t][4 * r4 + k] * linv - e[k]; o[t][4 * r4 + k] = v; ss += v * v; } }
;         ss += __shfl_xor(ss, 32);
;         const float rs = 0.8f / sqrtf(ss * (1.f / 128.f) + 1e-5f);
;         bf16* orow = MIX + (size_t)(tokbase + q0 + n) * D + 512 + h * 128;
; #pragma unroll
;         for (int t = 0; t < 4; ++t)
; #pragma unroll
;             for (int p2 = 0; p2 < 2; ++p2) {
;                 u32x2 eo[2];
; #pragma unroll
;                 for (int q = 0; q < 2; ++q) { const int r4 = 2 * p2 + q, dv = 32 * t + 8 * r4 + 4 * hi; const f32x4 w = *(const f32x4*)(subln + dv);
;                     eo[q].x = pk2(o[t][4 * r4] * rs * w.x, o[t][4 * r4 + 1] * rs * w.y); eo[q].y = pk2(o[t][4 * r4 + 2] * rs * w.z, o[t][4 * r4 + 3] * rs * w.w); }
;                 const auto sx = __builtin_amdgcn_permlane32_swap(eo[0].x, eo[1].x, false, false), sy = __builtin_amdgcn_permlane32_swap(eo[0].y, eo[1].y, false, false);
;                 const v4u ov = {sx[0], sy[0], sx[1], sy[1]};
;                 *(v4u*)(orow + 32 * t + 8 * (2 * p2 + hi)) = ov; }
	global_load_dwordx4 v[204:207], v[172:173], off offset:224
	global_load_dwordx4 v[208:211], v[172:173], off offset:256
	global_load_dwordx4 v[212:215], v[172:173], off offset:288
	global_load_dwordx4 v[216:219], v[172:173], off offset:320
	global_load_dwordx4 v[220:223], v[172:173], off offset:352
	global_load_dwordx4 v[224:227], v[172:173], off offset:384
	global_load_dwordx4 v[234:237], v[172:173], off offset:416
	global_load_dwordx4 v[238:241], v[172:173], off offset:448
	global_load_dwordx4 v[244:247], v[172:173], off offset:480
	v_pk_mul_f32 v[92:93], v[50:51], v[50:51]
	v_add_f32_e32 v68, v91, v68
	v_add_f32_e32 v68, v92, v68
	v_pk_mul_f32 v[94:95], v[40:41], v[40:41]
	v_add_f32_e32 v68, v93, v68
	v_add_f32_e32 v68, v94, v68
	v_pk_mul_f32 v[96:97], v[48:49], v[48:49]
	v_add_f32_e32 v68, v95, v68
	v_add_f32_e32 v68, v96, v68
	v_pk_mul_f32 v[98:99], v[44:45], v[44:45]
	v_add_f32_e32 v68, v97, v68
	v_add_f32_e32 v68, v98, v68
	v_pk_mul_f32 v[46:47], v[42:43], v[42:43]
	v_add_f32_e32 v68, v99, v68
	v_add_f32_e32 v46, v46, v68
	v_pk_mul_f32 v[102:103], v[36:37], v[36:37]
	v_add_f32_e32 v46, v47, v46
	v_add_f32_e32 v46, v102, v46
	v_pk_mul_f32 v[100:101], v[34:35], v[34:35]
	v_add_f32_e32 v46, v103, v46
	v_add_f32_e32 v46, v100, v46
	v_pk_mul_f32 v[106:107], v[38:39], v[38:39]
	v_add_f32_e32 v46, v101, v46
	v_add_f32_e32 v46, v106, v46
	v_pk_mul_f32 v[104:105], v[32:33], v[32:33]
	v_add_f32_e32 v46, v107, v46
	v_add_f32_e32 v46, v104, v46
	v_pk_mul_f32 v[114:115], v[24:25], v[24:25]
	v_add_f32_e32 v46, v105, v46
	v_add_f32_e32 v46, v114, v46
	v_pk_mul_f32 v[108:109], v[22:23], v[22:23]
	v_add_f32_e32 v46, v115, v46
	v_add_f32_e32 v46, v108, v46
	v_pk_mul_f32 v[28:29], v[26:27], v[26:27]
	v_add_f32_e32 v46, v109, v46
	v_add_f32_e32 v28, v28, v46
	v_pk_mul_f32 v[30:31], v[20:21], v[20:21]
	v_add_f32_e32 v28, v29, v28
	v_add_f32_e32 v28, v30, v28
	v_pk_mul_f32 v[118:119], v[18:19], v[18:19]
	v_add_f32_e32 v28, v31, v28
	v_add_f32_e32 v28, v118, v28
	v_pk_mul_f32 v[2:3], v[16:17], v[16:17]
	v_add_f32_e32 v28, v119, v28
	v_add_f32_e32 v2, v2, v28
	v_pk_mul_f32 v[120:121], v[4:5], v[4:5]
	v_add_f32_e32 v2, v3, v2
	v_add_f32_e32 v2, v120, v2
	v_pk_mul_f32 v[116:117], v[6:7], v[6:7]
	v_add_f32_e32 v2, v121, v2
	v_add_f32_e32 v2, v116, v2
	v_pk_mul_f32 v[8:9], v[0:1], v[0:1]
	v_add_f32_e32 v2, v117, v2
	v_add_f32_e32 v2, v8, v2
	v_pk_mul_f32 v[112:113], v[64:65], v[64:65]
	v_add_f32_e32 v2, v9, v2
	v_add_f32_e32 v2, v112, v2
	v_pk_mul_f32 v[134:135], v[66:67], v[66:67]
	v_add_f32_e32 v2, v113, v2
	v_add_f32_e32 v2, v134, v2
	v_pk_mul_f32 v[136:137], v[14:15], v[14:15]
	v_add_f32_e32 v2, v135, v2
	v_add_f32_e32 v2, v136, v2
	v_add_f32_e32 v2, v137, v2
	ds_bpermute_b32 v3, v165, v2
	s_lshl_b32 s4, s78, 1
	s_waitcnt lgkmcnt(0)
	v_add_f32_e32 v2, v2, v3
	v_fmamk_f32 v2, v2, 0x3c000000, v184
	v_mul_f32_e32 v3, 0x4f800000, v2
	v_cmp_gt_f32_e32 vcc, s73, v2
	s_nop 1
	v_cndmask_b32_e32 v8, v2, v3, vcc
	v_sqrt_f32_e32 v9, v8
	v_lshl_add_u64 v[2:3], v[174:175], 1, s[30:31]
	v_lshl_add_u64 v[2:3], v[2:3], 0, s[4:5]
	v_lshl_add_u64 v[2:3], v[2:3], 0, v[170:171]
	v_add_u32_e32 v28, -1, v9
	v_fma_f32 v29, -v28, v9, v8
	v_cmp_ge_f32_e64 s[0:1], 0, v29
	v_add_u32_e32 v29, 1, v9
	s_nop 0
	v_cndmask_b32_e64 v28, v9, v28, s[0:1]
	v_fma_f32 v9, -v29, v9, v8
	v_cmp_lt_f32_e64 s[0:1], 0, v9
	s_nop 1
	v_cndmask_b32_e64 v9, v28, v29, s[0:1]
	v_mul_f32_e32 v28, 0x37800000, v9
	v_cndmask_b32_e32 v9, v9, v28, vcc
	v_cmp_class_f32_e32 vcc, v8, v185
	s_nop 1
	v_cndmask_b32_e32 v8, v9, v8, vcc
	v_div_scale_f32 v9, s[0:1], v8, v8, s74
	v_rcp_f32_e32 v28, v9
	s_nop 0
	v_fma_f32 v29, -v9, v28, 1.0
	v_fmac_f32_e32 v28, v29, v28
	v_div_scale_f32 v29, vcc, s74, v8, s74
	v_mul_f32_e32 v30, v29, v28
	v_fma_f32 v31, -v9, v30, v29
	v_fmac_f32_e32 v30, v31, v28
	v_fma_f32 v9, -v9, v30, v29
	v_div_fmas_f32 v9, v9, v28, v30
	v_div_fixup_f32 v8, v9, v8, s74
	v_pk_mul_f32 v[28:29], v[142:143], v[8:9] op_sel_hi:[1,0]
	s_waitcnt vmcnt(15)
	v_pk_mul_f32 v[28:29], v[122:123], v[28:29]
	s_nop 0
	v_and_b32_sdwa v9, v29, v190 dst_sel:DWORD dst_unused:UNUSED_PAD src0_sel:WORD_1 src1_sel:DWORD
	v_and_b32_sdwa v30, v28, v190 dst_sel:DWORD dst_unused:UNUSED_PAD src0_sel:WORD_1 src1_sel:DWORD
	v_add3_u32 v9, v29, v9, s75
	v_add3_u32 v28, v28, v30, s75
	v_pk_mul_f32 v[30:31], v[138:139], v[8:9] op_sel_hi:[1,0]
	v_lshrrev_b32_e32 v28, 16, v28
	v_pk_mul_f32 v[30:31], v[124:125], v[30:31]
	v_and_or_b32 v28, v9, s76, v28
	v_and_b32_sdwa v9, v31, v190 dst_sel:DWORD dst_unused:UNUSED_PAD src0_sel:WORD_1 src1_sel:DWORD
	v_and_b32_sdwa v29, v30, v190 dst_sel:DWORD dst_unused:UNUSED_PAD src0_sel:WORD_1 src1_sel:DWORD
	v_add3_u32 v9, v31, v9, s75
	v_add3_u32 v29, v30, v29, s75
	v_pk_mul_f32 v[30:31], v[74:75], v[8:9] op_sel_hi:[1,0]
	v_lshrrev_b32_e32 v29, 16, v29
	s_waitcnt vmcnt(14)
	v_pk_mul_f32 v[10:11], v[10:11], v[30:31]
	v_and_or_b32 v29, v9, s76, v29
	v_and_b32_sdwa v30, v10, v190 dst_sel:DWORD dst_unused:UNUSED_PAD src0_sel:WORD_1 src1_sel:DWORD
	v_and_b32_sdwa v9, v11, v190 dst_sel:DWORD dst_unused:UNUSED_PAD src0_sel:WORD_1 src1_sel:DWORD
	v_add3_u32 v10, v10, v30, s75
	v_add3_u32 v9, v11, v9, s75
	v_lshrrev_b32_e32 v10, 16, v10
	v_and_or_b32 v30, v9, s76, v10
	v_pk_mul_f32 v[10:11], v[72:73], v[8:9] op_sel_hi:[1,0]
	s_nop 0
	v_permlane32_swap_b32_e32 v28, v30
	v_pk_mul_f32 v[10:11], v[12:13], v[10:11]
	s_nop 0
	v_and_b32_sdwa v12, v10, v190 dst_sel:DWORD dst_unused:UNUSED_PAD src0_sel:WORD_1 src1_sel:DWORD
	v_and_b32_sdwa v9, v11, v190 dst_sel:DWORD dst_unused:UNUSED_PAD src0_sel:WORD_1 src1_sel:DWORD
	v_add3_u32 v10, v10, v12, s75
	v_add3_u32 v9, v11, v9, s75
	v_lshrrev_b32_e32 v10, 16, v10
	v_and_or_b32 v31, v9, s76, v10
	s_nop 1
	v_permlane32_swap_b32_e32 v29, v31
	global_store_dwordx4 v[2:3], v[28:31], off offset:1024
	s_nop 0
	v_pk_mul_f32 v[46:47], v[62:63], v[8:9] op_sel_hi:[1,0]
	s_waitcnt vmcnt(14)
; __device__ __forceinline__ unsigned pk2(float lo, float hi) { return f2bf(lo) | (f2bf(hi) << 16); }
; __device__ __forceinline__ void attn_unit(ldsp lds, const bf16* QK, const bf16* VT, bf16* MIX, const float* subln, float lam, int tokbase, int L, int h, int qb, int tid, int wid, int lane) {
;     ...
; #pragma unroll
;         for (int t = 0; t < 4; ++t)
; #pragma unroll
;             for (int p2 = 0; p2 < 2; ++p2) {
;                 u32x2 eo[2];
; #pragma unroll
;                 for (int q = 0; q < 2; ++q) { const int r4 = 2 * p2 + q, dv = 32 * t + 8 * r4 + 4 * hi; const f32x4 w = *(const f32x4*)(subln + dv);
;                     eo[q].x = pk2(o[t][4 * r4] * rs * w.x, o[t][4 * r4 + 1] * rs * w.y); eo[q].y = pk2(o[t][4 * r4 + 2] * rs * w.z, o[t][4 * r4 + 3] * rs * w.w); }
;                 const auto sx = __builtin_amdgcn_permlane32_swap(eo[0].x, eo[1].x, false, false), sy = __builtin_amdgcn_permlane32_swap(eo[0].y, eo[1].y, false, false);
;                 const v4u ov = {sx[0], sy[0], sx[1], sy[1]};
;                 *(v4u*)(orow + 32 * t + 8 * (2 * p2 + hi)) = ov; }
	v_pk_mul_f32 v[10:11], v[148:149], v[46:47]
	s_nop 0
	v_and_b32_sdwa v9, v11, v190 dst_sel:DWORD dst_unused:UNUSED_PAD src0_sel:WORD_1 src1_sel:DWORD
	v_and_b32_sdwa v46, v10, v190 dst_sel:DWORD dst_unused:UNUSED_PAD src0_sel:WORD_1 src1_sel:DWORD
	v_add3_u32 v9, v11, v9, s75
	v_add3_u32 v10, v10, v46, s75
	v_pk_mul_f32 v[46:47], v[70:71], v[8:9] op_sel_hi:[1,0]
	v_lshrrev_b32_e32 v10, 16, v10
	v_pk_mul_f32 v[12:13], v[150:151], v[46:47]
	v_and_or_b32 v10, v9, s76, v10
	v_and_b32_sdwa v9, v13, v190 dst_sel:DWORD dst_unused:UNUSED_PAD src0_sel:WORD_1 src1_sel:DWORD
	v_and_b32_sdwa v11, v12, v190 dst_sel:DWORD dst_unused:UNUSED_PAD src0_sel:WORD_1 src1_sel:DWORD
	v_add3_u32 v9, v13, v9, s75
	v_add3_u32 v11, v12, v11, s75
	v_pk_mul_f32 v[12:13], v[60:61], v[8:9] op_sel_hi:[1,0]
	v_lshrrev_b32_e32 v11, 16, v11
	s_waitcnt vmcnt(13)
	v_pk_mul_f32 v[12:13], v[152:153], v[12:13]
	v_and_or_b32 v11, v9, s76, v11
	v_and_b32_sdwa v9, v13, v190 dst_sel:DWORD dst_unused:UNUSED_PAD src0_sel:WORD_1 src1_sel:DWORD
	v_and_b32_sdwa v28, v12, v190 dst_sel:DWORD dst_unused:UNUSED_PAD src0_sel:WORD_1 src1_sel:DWORD
	v_add3_u32 v9, v13, v9, s75
	v_add3_u32 v12, v12, v28, s75
	v_pk_mul_f32 v[28:29], v[58:59], v[8:9] op_sel_hi:[1,0]
	v_lshrrev_b32_e32 v12, 16, v12
	v_pk_mul_f32 v[28:29], v[154:155], v[28:29]
	v_and_or_b32 v12, v9, s76, v12
	v_and_b32_sdwa v13, v28, v190 dst_sel:DWORD dst_unused:UNUSED_PAD src0_sel:WORD_1 src1_sel:DWORD
	v_and_b32_sdwa v9, v29, v190 dst_sel:DWORD dst_unused:UNUSED_PAD src0_sel:WORD_1 src1_sel:DWORD
	v_add3_u32 v13, v28, v13, s75
	v_add3_u32 v9, v29, v9, s75
	v_lshrrev_b32_e32 v13, 16, v13
	v_and_or_b32 v13, v9, s76, v13
	v_permlane32_swap_b32_e32 v10, v12
	s_nop 0
	v_permlane32_swap_b32_e32 v11, v13
	global_store_dwordx4 v[2:3], v[10:13], off offset:1056
	s_nop 0
	v_pk_mul_f32 v[46:47], v[54:55], v[8:9] op_sel_hi:[1,0]
	v_pk_mul_f32 v[52:53], v[52:53], v[8:9] op_sel_hi:[1,0]
	v_pk_mul_f32 v[54:55], v[56:57], v[8:9] op_sel_hi:[1,0]
	s_waitcnt vmcnt(13)
	v_pk_mul_f32 v[12:13], v[158:159], v[52:53]
	s_waitcnt vmcnt(12)
	v_pk_mul_f32 v[28:29], v[196:197], v[54:55]
	v_pk_mul_f32 v[10:11], v[156:157], v[46:47]
	v_and_b32_sdwa v52, v12, v190 dst_sel:DWORD dst_unused:UNUSED_PAD src0_sel:WORD_1 src1_sel:DWORD
	v_and_b32_sdwa v54, v28, v190 dst_sel:DWORD dst_unused:UNUSED_PAD src0_sel:WORD_1 src1_sel:DWORD
	v_and_b32_sdwa v9, v11, v190 dst_sel:DWORD dst_unused:UNUSED_PAD src0_sel:WORD_1 src1_sel:DWORD
	v_and_b32_sdwa v47, v13, v190 dst_sel:DWORD dst_unused:UNUSED_PAD src0_sel:WORD_1 src1_sel:DWORD
	v_and_b32_sdwa v53, v29, v190 dst_sel:DWORD dst_unused:UNUSED_PAD src0_sel:WORD_1 src1_sel:DWORD
	v_add3_u32 v12, v12, v52, s75
	v_add3_u32 v28, v28, v54, s75
	v_add3_u32 v9, v11, v9, s75
	v_add3_u32 v11, v13, v47, s75
	v_add3_u32 v13, v29, v53, s75
	v_lshrrev_b32_e32 v12, 16, v12
	v_lshrrev_b32_e32 v28, 16, v28
	v_and_b32_sdwa v46, v10, v190 dst_sel:DWORD dst_unused:UNUSED_PAD src0_sel:WORD_1 src1_sel:DWORD
	v_and_or_b32 v11, v11, s76, v12
	v_and_or_b32 v12, v13, s76, v28
	v_pk_mul_f32 v[28:29], v[50:51], v[8:9] op_sel_hi:[1,0]
	v_add3_u32 v10, v10, v46, s75
	v_pk_mul_f32 v[28:29], v[198:199], v[28:29]
	v_lshrrev_b32_e32 v10, 16, v10
	v_and_b32_sdwa v13, v28, v190 dst_sel:DWORD dst_unused:UNUSED_PAD src0_sel:WORD_1 src1_sel:DWORD
	v_and_or_b32 v10, v9, s76, v10
	v_and_b32_sdwa v9, v29, v190 dst_sel:DWORD dst_unused:UNUSED_PAD src0_sel:WORD_1 src1_sel:DWORD
	v_add3_u32 v13, v28, v13, s75
	v_add3_u32 v9, v29, v9, s75
	v_lshrrev_b32_e32 v13, 16, v13
	v_and_or_b32 v13, v9, s76, v13
	v_permlane32_swap_b32_e32 v10, v12
	s_nop 0
	v_permlane32_swap_b32_e32 v11, v13
	global_store_dwordx4 v[2:3], v[10:13], off offset:1088
	s_nop 0
	v_pk_mul_f32 v[40:41], v[40:41], v[8:9] op_sel_hi:[1,0]
	v_pk_mul_f32 v[46:47], v[48:49], v[8:9] op_sel_hi:[1,0]
	v_pk_mul_f32 v[44:45], v[44:45], v[8:9] op_sel_hi:[1,0]
	v_pk_mul_f32 v[42:43], v[42:43], v[8:9] op_sel_hi:[1,0]
	s_waitcnt vmcnt(12)
	v_pk_mul_f32 v[10:11], v[200:201], v[40:41]
	v_pk_mul_f32 v[12:13], v[202:203], v[46:47]
	s_waitcnt vmcnt(11)
	v_pk_mul_f32 v[28:29], v[204:205], v[44:45]
	v_pk_mul_f32 v[30:31], v[206:207], v[42:43]
	v_and_b32_sdwa v40, v10, v190 dst_sel:DWORD dst_unused:UNUSED_PAD src0_sel:WORD_1 src1_sel:DWORD
	v_and_b32_sdwa v42, v12, v190 dst_sel:DWORD dst_unused:UNUSED_PAD src0_sel:WORD_1 src1_sel:DWORD
	v_and_b32_sdwa v44, v28, v190 dst_sel:DWORD dst_unused:UNUSED_PAD src0_sel:WORD_1 src1_sel:DWORD
	v_and_b32_sdwa v46, v30, v190 dst_sel:DWORD dst_unused:UNUSED_PAD src0_sel:WORD_1 src1_sel:DWORD
	v_and_b32_sdwa v9, v11, v190 dst_sel:DWORD dst_unused:UNUSED_PAD src0_sel:WORD_1 src1_sel:DWORD
	v_and_b32_sdwa v41, v13, v190 dst_sel:DWORD dst_unused:UNUSED_PAD src0_sel:WORD_1 src1_sel:DWORD
	v_and_b32_sdwa v43, v29, v190 dst_sel:DWORD dst_unused:UNUSED_PAD src0_sel:WORD_1 src1_sel:DWORD
	v_and_b32_sdwa v45, v31, v190 dst_sel:DWORD dst_unused:UNUSED_PAD src0_sel:WORD_1 src1_sel:DWORD
	v_add3_u32 v10, v10, v40, s75
	v_add3_u32 v12, v12, v42, s75
	v_add3_u32 v28, v28, v44, s75
	v_add3_u32 v30, v30, v46, s75
	v_add3_u32 v9, v11, v9, s75
	v_add3_u32 v11, v13, v41, s75
	v_add3_u32 v13, v29, v43, s75
	v_add3_u32 v29, v31, v45, s75
	v_lshrrev_b32_e32 v10, 16, v10
	v_lshrrev_b32_e32 v12, 16, v12
	v_lshrrev_b32_e32 v28, 16, v28
	v_lshrrev_b32_e32 v30, 16, v30
	v_and_or_b32 v10, v9, s76, v10
	v_and_or_b32 v11, v11, s76, v12
	v_and_or_b32 v12, v13, s76, v28
	v_and_or_b32 v13, v29, s76, v30
	s_nop 0
	v_permlane32_swap_b32_e32 v10, v12
	v_permlane32_swap_b32_e32 v11, v13
	global_store_dwordx4 v[2:3], v[10:13], off offset:1120
	s_nop 0
	v_pk_mul_f32 v[36:37], v[36:37], v[8:9] op_sel_hi:[1,0]
	v_pk_mul_f32 v[34:35], v[34:35], v[8:9] op_sel_hi:[1,0]
	v_pk_mul_f32 v[38:39], v[38:39], v[8:9] op_sel_hi:[1,0]
	v_pk_mul_f32 v[32:33], v[32:33], v[8:9] op_sel_hi:[1,0]
	s_waitcnt vmcnt(11)
; __device__ __forceinline__ unsigned pk2(float lo, float hi) { return f2bf(lo) | (f2bf(hi) << 16); }
; __device__ __forceinline__ void attn_unit(ldsp lds, const bf16* QK, const bf16* VT, bf16* MIX, const float* subln, float lam, int tokbase, int L, int h, int qb, int tid, int wid, int lane) {
;     ...
; #pragma unroll
;         for (int t = 0; t < 4; ++t)
; #pragma unroll
;             for (int p2 = 0; p2 < 2; ++p2) {
;                 u32x2 eo[2];
; #pragma unroll
;                 for (int q = 0; q < 2; ++q) { const int r4 = 2 * p2 + q, dv = 32 * t + 8 * r4 + 4 * hi; const f32x4 w = *(const f32x4*)(subln + dv);
;                     eo[q].x = pk2(o[t][4 * r4] * rs * w.x, o[t][4 * r4 + 1] * rs * w.y); eo[q].y = pk2(o[t][4 * r4 + 2] * rs * w.z, o[t][4 * r4 + 3] * rs * w.w); }
;                 const auto sx = __builtin_amdgcn_permlane32_swap(eo[0].x, eo[1].x, false, false), sy = __builtin_amdgcn_permlane32_swap(eo[0].y, eo[1].y, false, false);
;                 const v4u ov = {sx[0], sy[0], sx[1], sy[1]};
;                 *(v4u*)(orow + 32 * t + 8 * (2 * p2 + hi)) = ov; }
	v_pk_mul_f32 v[10:11], v[208:209], v[36:37]
	v_pk_mul_f32 v[12:13], v[210:211], v[34:35]
	s_waitcnt vmcnt(10)
	v_pk_mul_f32 v[28:29], v[212:213], v[38:39]
	v_pk_mul_f32 v[30:31], v[214:215], v[32:33]
	v_and_b32_sdwa v32, v10, v190 dst_sel:DWORD dst_unused:UNUSED_PAD src0_sel:WORD_1 src1_sel:DWORD
	v_and_b32_sdwa v34, v12, v190 dst_sel:DWORD dst_unused:UNUSED_PAD src0_sel:WORD_1 src1_sel:DWORD
	v_and_b32_sdwa v36, v28, v190 dst_sel:DWORD dst_unused:UNUSED_PAD src0_sel:WORD_1 src1_sel:DWORD
	v_and_b32_sdwa v38, v30, v190 dst_sel:DWORD dst_unused:UNUSED_PAD src0_sel:WORD_1 src1_sel:DWORD
	v_and_b32_sdwa v9, v11, v190 dst_sel:DWORD dst_unused:UNUSED_PAD src0_sel:WORD_1 src1_sel:DWORD
	v_and_b32_sdwa v33, v13, v190 dst_sel:DWORD dst_unused:UNUSED_PAD src0_sel:WORD_1 src1_sel:DWORD
	v_and_b32_sdwa v35, v29, v190 dst_sel:DWORD dst_unused:UNUSED_PAD src0_sel:WORD_1 src1_sel:DWORD
	v_and_b32_sdwa v37, v31, v190 dst_sel:DWORD dst_unused:UNUSED_PAD src0_sel:WORD_1 src1_sel:DWORD
	v_add3_u32 v10, v10, v32, s75
	v_add3_u32 v12, v12, v34, s75
	v_add3_u32 v28, v28, v36, s75
	v_add3_u32 v30, v30, v38, s75
	v_add3_u32 v9, v11, v9, s75
	v_add3_u32 v11, v13, v33, s75
	v_add3_u32 v13, v29, v35, s75
	v_add3_u32 v29, v31, v37, s75
	v_lshrrev_b32_e32 v10, 16, v10
	v_lshrrev_b32_e32 v12, 16, v12
	v_lshrrev_b32_e32 v28, 16, v28
	v_lshrrev_b32_e32 v30, 16, v30
	v_and_or_b32 v10, v9, s76, v10
	v_and_or_b32 v11, v11, s76, v12
	v_and_or_b32 v12, v13, s76, v28
	v_and_or_b32 v13, v29, s76, v30
	s_nop 0
	v_permlane32_swap_b32_e32 v10, v12
	v_permlane32_swap_b32_e32 v11, v13
	global_store_dwordx4 v[2:3], v[10:13], off offset:1152
	s_nop 0
	v_pk_mul_f32 v[24:25], v[24:25], v[8:9] op_sel_hi:[1,0]
	v_pk_mul_f32 v[22:23], v[22:23], v[8:9] op_sel_hi:[1,0]
	v_pk_mul_f32 v[26:27], v[26:27], v[8:9] op_sel_hi:[1,0]
	v_pk_mul_f32 v[20:21], v[20:21], v[8:9] op_sel_hi:[1,0]
	s_waitcnt vmcnt(10)
	v_pk_mul_f32 v[10:11], v[216:217], v[24:25]
	v_pk_mul_f32 v[12:13], v[218:219], v[22:23]
	s_waitcnt vmcnt(9)
	v_pk_mul_f32 v[22:23], v[220:221], v[26:27]
	v_pk_mul_f32 v[20:21], v[222:223], v[20:21]
	v_and_b32_sdwa v24, v10, v190 dst_sel:DWORD dst_unused:UNUSED_PAD src0_sel:WORD_1 src1_sel:DWORD
	v_and_b32_sdwa v26, v12, v190 dst_sel:DWORD dst_unused:UNUSED_PAD src0_sel:WORD_1 src1_sel:DWORD
	v_and_b32_sdwa v28, v22, v190 dst_sel:DWORD dst_unused:UNUSED_PAD src0_sel:WORD_1 src1_sel:DWORD
	v_and_b32_sdwa v30, v20, v190 dst_sel:DWORD dst_unused:UNUSED_PAD src0_sel:WORD_1 src1_sel:DWORD
	v_and_b32_sdwa v9, v11, v190 dst_sel:DWORD dst_unused:UNUSED_PAD src0_sel:WORD_1 src1_sel:DWORD
	v_and_b32_sdwa v25, v13, v190 dst_sel:DWORD dst_unused:UNUSED_PAD src0_sel:WORD_1 src1_sel:DWORD
	v_and_b32_sdwa v27, v23, v190 dst_sel:DWORD dst_unused:UNUSED_PAD src0_sel:WORD_1 src1_sel:DWORD
	v_and_b32_sdwa v29, v21, v190 dst_sel:DWORD dst_unused:UNUSED_PAD src0_sel:WORD_1 src1_sel:DWORD
	v_add3_u32 v10, v10, v24, s75
	v_add3_u32 v12, v12, v26, s75
	v_add3_u32 v22, v22, v28, s75
	v_add3_u32 v20, v20, v30, s75
	v_add3_u32 v9, v11, v9, s75
	v_add3_u32 v11, v13, v25, s75
	v_add3_u32 v13, v23, v27, s75
	v_add3_u32 v21, v21, v29, s75
	v_lshrrev_b32_e32 v10, 16, v10
	v_lshrrev_b32_e32 v12, 16, v12
	v_lshrrev_b32_e32 v22, 16, v22
	v_lshrrev_b32_e32 v20, 16, v20
	v_and_or_b32 v10, v9, s76, v10
	v_and_or_b32 v11, v11, s76, v12
	v_and_or_b32 v12, v13, s76, v22
	v_and_or_b32 v13, v21, s76, v20
	s_nop 0
	v_permlane32_swap_b32_e32 v10, v12
	v_permlane32_swap_b32_e32 v11, v13
	global_store_dwordx4 v[2:3], v[10:13], off offset:1184
	s_nop 0
	v_pk_mul_f32 v[18:19], v[18:19], v[8:9] op_sel_hi:[1,0]
	v_pk_mul_f32 v[16:17], v[16:17], v[8:9] op_sel_hi:[1,0]
	v_pk_mul_f32 v[4:5], v[4:5], v[8:9] op_sel_hi:[1,0]
	v_pk_mul_f32 v[6:7], v[6:7], v[8:9] op_sel_hi:[1,0]
	s_waitcnt vmcnt(9)
; __device__ __forceinline__ unsigned pk2(float lo, float hi) { return f2bf(lo) | (f2bf(hi) << 16); }
; __device__ __forceinline__ void attn_unit(ldsp lds, const bf16* QK, const bf16* VT, bf16* MIX, const float* subln, float lam, int tokbase, int L, int h, int qb, int tid, int wid, int lane) {
;     ...
; #pragma unroll
;         for (int t = 0; t < 4; ++t)
; #pragma unroll
;             for (int p2 = 0; p2 < 2; ++p2) {
;                 u32x2 eo[2];
; #pragma unroll
;                 for (int q = 0; q < 2; ++q) { const int r4 = 2 * p2 + q, dv = 32 * t + 8 * r4 + 4 * hi; const f32x4 w = *(const f32x4*)(subln + dv);
;                     eo[q].x = pk2(o[t][4 * r4] * rs * w.x, o[t][4 * r4 + 1] * rs * w.y); eo[q].y = pk2(o[t][4 * r4 + 2] * rs * w.z, o[t][4 * r4 + 3] * rs * w.w); }
;                 const auto sx = __builtin_amdgcn_permlane32_swap(eo[0].x, eo[1].x, false, false), sy = __builtin_amdgcn_permlane32_swap(eo[0].y, eo[1].y, false, false);
;                 const v4u ov = {sx[0], sy[0], sx[1], sy[1]};
;                 *(v4u*)(orow + 32 * t + 8 * (2 * p2 + hi)) = ov; }
	v_pk_mul_f32 v[10:11], v[224:225], v[18:19]
	v_pk_mul_f32 v[12:13], v[226:227], v[16:17]
	s_waitcnt vmcnt(8)
	v_pk_mul_f32 v[4:5], v[234:235], v[4:5]
	v_pk_mul_f32 v[6:7], v[236:237], v[6:7]
	v_and_b32_sdwa v9, v11, v190 dst_sel:DWORD dst_unused:UNUSED_PAD src0_sel:WORD_1 src1_sel:DWORD
	v_and_b32_sdwa v16, v10, v190 dst_sel:DWORD dst_unused:UNUSED_PAD src0_sel:WORD_1 src1_sel:DWORD
	v_and_b32_sdwa v17, v13, v190 dst_sel:DWORD dst_unused:UNUSED_PAD src0_sel:WORD_1 src1_sel:DWORD
	v_and_b32_sdwa v18, v12, v190 dst_sel:DWORD dst_unused:UNUSED_PAD src0_sel:WORD_1 src1_sel:DWORD
	v_and_b32_sdwa v19, v5, v190 dst_sel:DWORD dst_unused:UNUSED_PAD src0_sel:WORD_1 src1_sel:DWORD
	v_and_b32_sdwa v20, v4, v190 dst_sel:DWORD dst_unused:UNUSED_PAD src0_sel:WORD_1 src1_sel:DWORD
	v_and_b32_sdwa v22, v6, v190 dst_sel:DWORD dst_unused:UNUSED_PAD src0_sel:WORD_1 src1_sel:DWORD
	v_and_b32_sdwa v21, v7, v190 dst_sel:DWORD dst_unused:UNUSED_PAD src0_sel:WORD_1 src1_sel:DWORD
	v_add3_u32 v9, v11, v9, s75
	v_add3_u32 v10, v10, v16, s75
	v_add3_u32 v11, v13, v17, s75
	v_add3_u32 v12, v12, v18, s75
	v_add3_u32 v13, v5, v19, s75
	v_add3_u32 v4, v4, v20, s75
	v_add3_u32 v5, v6, v22, s75
	v_add3_u32 v7, v7, v21, s75
	v_lshrrev_b32_e32 v6, 16, v10
	v_lshrrev_b32_e32 v10, 16, v12
	v_lshrrev_b32_e32 v12, 16, v4
	v_lshrrev_b32_e32 v16, 16, v5
	v_and_or_b32 v4, v9, s76, v6
	v_and_or_b32 v5, v11, s76, v10
	v_and_or_b32 v6, v13, s76, v12
	v_and_or_b32 v7, v7, s76, v16
	s_nop 0
	v_permlane32_swap_b32_e32 v4, v6
	v_permlane32_swap_b32_e32 v5, v7
	global_store_dwordx4 v[2:3], v[4:7], off offset:1216
	s_nop 0
	v_pk_mul_f32 v[0:1], v[0:1], v[8:9] op_sel_hi:[1,0]
	v_pk_mul_f32 v[16:17], v[64:65], v[8:9] op_sel_hi:[1,0]
	v_pk_mul_f32 v[18:19], v[66:67], v[8:9] op_sel_hi:[1,0]
	v_pk_mul_f32 v[8:9], v[14:15], v[8:9] op_sel_hi:[1,0]
	s_waitcnt vmcnt(8)
	v_pk_mul_f32 v[0:1], v[238:239], v[0:1]
	v_pk_mul_f32 v[4:5], v[240:241], v[16:17]
	s_waitcnt vmcnt(7)
	v_pk_mul_f32 v[6:7], v[244:245], v[18:19]
	v_pk_mul_f32 v[8:9], v[246:247], v[8:9]
	v_and_b32_sdwa v11, v0, v190 dst_sel:DWORD dst_unused:UNUSED_PAD src0_sel:WORD_1 src1_sel:DWORD
	v_and_b32_sdwa v13, v4, v190 dst_sel:DWORD dst_unused:UNUSED_PAD src0_sel:WORD_1 src1_sel:DWORD
	v_and_b32_sdwa v15, v6, v190 dst_sel:DWORD dst_unused:UNUSED_PAD src0_sel:WORD_1 src1_sel:DWORD
	v_and_b32_sdwa v17, v8, v190 dst_sel:DWORD dst_unused:UNUSED_PAD src0_sel:WORD_1 src1_sel:DWORD
	v_and_b32_sdwa v10, v1, v190 dst_sel:DWORD dst_unused:UNUSED_PAD src0_sel:WORD_1 src1_sel:DWORD
	v_and_b32_sdwa v12, v5, v190 dst_sel:DWORD dst_unused:UNUSED_PAD src0_sel:WORD_1 src1_sel:DWORD
	v_and_b32_sdwa v14, v7, v190 dst_sel:DWORD dst_unused:UNUSED_PAD src0_sel:WORD_1 src1_sel:DWORD
	v_and_b32_sdwa v16, v9, v190 dst_sel:DWORD dst_unused:UNUSED_PAD src0_sel:WORD_1 src1_sel:DWORD
	v_add3_u32 v0, v0, v11, s75
	v_add3_u32 v4, v4, v13, s75
	v_add3_u32 v6, v6, v15, s75
	v_add3_u32 v8, v8, v17, s75
	v_add3_u32 v1, v1, v10, s75
	v_add3_u32 v5, v5, v12, s75
	v_add3_u32 v7, v7, v14, s75
	v_add3_u32 v9, v9, v16, s75
	v_lshrrev_b32_e32 v0, 16, v0
	v_lshrrev_b32_e32 v10, 16, v4
	v_lshrrev_b32_e32 v6, 16, v6
	v_lshrrev_b32_e32 v8, 16, v8
	v_and_or_b32 v4, v1, s76, v0
	v_and_or_b32 v5, v5, s76, v10
	v_and_or_b32 v6, v7, s76, v6
	v_and_or_b32 v7, v9, s76, v8
	s_nop 0
	v_permlane32_swap_b32_e32 v4, v6
	v_permlane32_swap_b32_e32 v5, v7
	global_store_dwordx4 v[2:3], v[4:7], off offset:1248
	s_branch .LBB0_999
